# v79 + FFN-up tile loop keeps the lead/trail stagger through the epilogue (lead aligns only on the last tile, trail re-stagger barrier removed)
# baseline (speedup 1.0000x reference)
; #define PG8_STAGE(bufoff, gbase, voff) do { _Pragma("unroll") for (int _i = 0; _i < 2; ++_i) \
;         __builtin_amdgcn_global_load_lds((const unsigned*)((const char*)(gbase) + (voff)[_i]), (PG8_LAS unsigned*)(lds + (bufoff) + ldsw + _i * 8192), 16, 0, 0); } while (0)
; #define PG8_LDA(dst, b, h) do { _Pragma("unroll") for (int m = 0; m < 4; ++m) _Pragma("unroll") for (int k = 0; k < 2; ++k) dst[m][k] = *(const PG8_LAS bf16x8*)(lds + PG8_SA(b, h) + aoff + m * 2048 + k * 1024); } while (0)
; #define PG8_LDB(dst, b, h) do { _Pragma("unroll") for (int n = 0; n < 2; ++n) _Pragma("unroll") for (int k = 0; k < 2; ++k) dst[n][k] = *(const PG8_LAS bf16x8*)(lds + PG8_SB(b, h) + boff + n * 2048 + k * 1024); } while (0)
; #define PG8_MMA(ai, bj, At, Bt) do { __builtin_amdgcn_s_setprio(1); _Pragma("unroll") for (int m = 0; m < 4; ++m) _Pragma("unroll") for (int n = 0; n < 2; ++n) _Pragma("unroll") for (int k = 0; k < 2; ++k) \
;         acc[ai][bj][m][n] = __builtin_amdgcn_mfma_f32_16x16x32_bf16(Bt[n][k], At[m][k], acc[ai][bj][m][n], 0, 0, 0); __builtin_amdgcn_s_setprio(0); } while (0)
; #define PG8_WAIT_V(n) asm volatile("s_waitcnt vmcnt(" #n ")" ::: "memory")
; #define PG8_WAIT_L(n) asm volatile("s_waitcnt lgkmcnt(" #n ")" ::: "memory")
; #define PG8_BAR __builtin_amdgcn_s_barrier()
; #define PG8_SCHED __builtin_amdgcn_sched_barrier(0)
; template <class Epi, class Sched, bool ALIGN_EPI = false, bool SP2 = false>
; __device__ __forceinline__ void gemm_phase(PG8_LAS unsigned char* lds, const Gemm g, const Sched& S, const Epi& E) {
;     ...
;             PG8_LDB(B0, 0, 0); PG8_LDB(B1, 0, 1); PG8_SCHED; PG8_LDA(At, 0, 0); PG8_STAGE(PG8_SA(1, 1), a1 + hstep, voffA);
;             PG8_WAIT_V(8); PG8_WAIT_L(0); PG8_BAR; PG8_MMA(0, 0, At, B0); PG8_MMA(0, 1, At, B1); PG8_BAR; PG8_SCHED;
;             PG8_LDA(At, 0, 1); PG8_STAGE(PG8_SB(0, 0), b2, voffB); PG8_STAGE(PG8_SB(0, 1), b2 + hstep, voffB); PG8_STAGE(PG8_SA(0, 0), a2, voffA);
;             PG8_WAIT_V(8); PG8_WAIT_L(0); PG8_BAR; PG8_MMA(1, 0, At, B0); PG8_MMA(1, 1, At, B1); PG8_BAR; PG8_SCHED;
.LBB0_1356:
	s_add_u32 s20, s18, 0x4000
	s_addc_u32 s21, s19, 0
	s_cmp_eq_u32 s68, 12
	s_cselect_b32 s64, s40, s20
	s_cselect_b32 s65, s11, s21
	s_cselect_b32 s62, s61, s66
	s_cselect_b32 s63, s9, s67
	s_add_u32 s20, s64, 0x8000
	s_addc_u32 s21, s65, 0
	s_add_i32 s69, 0, 0x10000
	s_add_i32 s72, 0, 0x14000
	v_add_u32_e32 v140, s69, v162
	v_add_u32_e32 v160, s72, v162
	ds_read_b128 v[128:131], v140
	ds_read_b128 v[132:135], v140 offset:1024
	ds_read_b128 v[136:139], v140 offset:2048
	ds_read_b128 v[140:143], v140 offset:3072
	ds_read_b128 v[156:159], v160
	ds_read_b128 v[164:167], v160 offset:1024
	ds_read_b128 v[168:171], v160 offset:2048
	ds_read_b128 v[172:175], v160 offset:3072
	s_add_i32 m0, s37, 0xc000
	ds_read_b128 v[176:179], v163
	ds_read_b128 v[180:183], v163 offset:1024
	ds_read_b128 v[184:187], v163 offset:2048
	ds_read_b128 v[188:191], v163 offset:3072
	ds_read_b128 v[192:195], v163 offset:4096
	ds_read_b128 v[196:199], v163 offset:5120
	ds_read_b128 v[200:203], v163 offset:6144
	ds_read_b128 v[204:207], v163 offset:7168
	global_load_lds_dwordx4 v152, s[18:19]
	s_add_i32 m0, s37, 0xe000
	s_nop 0
	global_load_lds_dwordx4 v154, s[18:19]
	s_waitcnt vmcnt(8) lgkmcnt(0)
	s_barrier
	v_mfma_f32_16x16x32_bf16 v[124:127], v[128:131], v[176:179], v[124:127]
	v_mfma_f32_16x16x32_bf16 v[120:123], v[136:139], v[176:179], v[120:123]
	v_mfma_f32_16x16x32_bf16 v[108:111], v[128:131], v[184:187], v[108:111]
	v_mfma_f32_16x16x32_bf16 v[104:107], v[136:139], v[184:187], v[104:107]
	v_mfma_f32_16x16x32_bf16 v[92:95], v[128:131], v[192:195], v[92:95]
	v_mfma_f32_16x16x32_bf16 v[88:91], v[136:139], v[192:195], v[88:91]
	v_mfma_f32_16x16x32_bf16 v[76:79], v[128:131], v[200:203], v[76:79]
	v_mfma_f32_16x16x32_bf16 v[72:75], v[136:139], v[200:203], v[72:75]
	v_mfma_f32_16x16x32_bf16 v[124:127], v[132:135], v[180:183], v[124:127]
	v_mfma_f32_16x16x32_bf16 v[120:123], v[140:143], v[180:183], v[120:123]
	v_mfma_f32_16x16x32_bf16 v[108:111], v[132:135], v[188:191], v[108:111]
	v_mfma_f32_16x16x32_bf16 v[104:107], v[140:143], v[188:191], v[104:107]
	v_mfma_f32_16x16x32_bf16 v[92:95], v[132:135], v[196:199], v[92:95]
	v_mfma_f32_16x16x32_bf16 v[88:91], v[140:143], v[196:199], v[88:91]
	v_mfma_f32_16x16x32_bf16 v[76:79], v[132:135], v[204:207], v[76:79]
	v_mfma_f32_16x16x32_bf16 v[72:75], v[140:143], v[204:207], v[72:75]
	v_mfma_f32_16x16x32_bf16 v[116:119], v[156:159], v[176:179], v[116:119]
	v_mfma_f32_16x16x32_bf16 v[112:115], v[168:171], v[176:179], v[112:115]
	v_mfma_f32_16x16x32_bf16 v[100:103], v[156:159], v[184:187], v[100:103]
	v_mfma_f32_16x16x32_bf16 v[96:99], v[168:171], v[184:187], v[96:99]
	v_mfma_f32_16x16x32_bf16 v[84:87], v[156:159], v[192:195], v[84:87]
	v_mfma_f32_16x16x32_bf16 v[80:83], v[168:171], v[192:195], v[80:83]
	v_mfma_f32_16x16x32_bf16 v[68:71], v[156:159], v[200:203], v[68:71]
	v_mfma_f32_16x16x32_bf16 v[64:67], v[168:171], v[200:203], v[64:67]
	v_mfma_f32_16x16x32_bf16 v[116:119], v[164:167], v[180:183], v[116:119]
	v_mfma_f32_16x16x32_bf16 v[112:115], v[172:175], v[180:183], v[112:115]
	v_mfma_f32_16x16x32_bf16 v[100:103], v[164:167], v[188:191], v[100:103]
	v_mfma_f32_16x16x32_bf16 v[96:99], v[172:175], v[188:191], v[96:99]
	v_mfma_f32_16x16x32_bf16 v[84:87], v[164:167], v[196:199], v[84:87]
	v_mfma_f32_16x16x32_bf16 v[80:83], v[172:175], v[196:199], v[80:83]
	v_mfma_f32_16x16x32_bf16 v[68:71], v[164:167], v[204:207], v[68:71]
	v_mfma_f32_16x16x32_bf16 v[64:67], v[172:175], v[204:207], v[64:67]
	s_barrier
	s_add_i32 s69, s69, s30
	s_mov_b32 m0, s69
	ds_read_b128 v[176:179], v163 offset:16384
	ds_read_b128 v[180:183], v163 offset:17408
	ds_read_b128 v[184:187], v163 offset:18432
	ds_read_b128 v[188:191], v163 offset:19456
	ds_read_b128 v[192:195], v163 offset:20480
	ds_read_b128 v[196:199], v163 offset:21504
	ds_read_b128 v[200:203], v163 offset:22528
	ds_read_b128 v[204:207], v163 offset:23552
	global_load_lds_dwordx4 v148, s[62:63]
	s_add_i32 m0, s69, 0x2000
	s_add_u32 s70, s62, 0x4000
	s_addc_u32 s71, s63, 0
	s_add_i32 s69, s72, s30
	global_load_lds_dwordx4 v144, s[62:63]
	s_mov_b32 m0, s69
	s_nop 0
	global_load_lds_dwordx4 v148, s[70:71]
	s_add_i32 m0, s69, 0x2000
	s_nop 0
	global_load_lds_dwordx4 v144, s[70:71]
	s_mov_b32 m0, s37
	s_nop 0
	global_load_lds_dwordx4 v150, s[64:65]
	s_mov_b32 m0, s39
	s_nop 0
	global_load_lds_dwordx4 v146, s[64:65]
	s_waitcnt vmcnt(8) lgkmcnt(0)
	s_barrier
	v_mfma_f32_16x16x32_bf16 v[60:63], v[128:131], v[176:179], v[60:63]
	v_mfma_f32_16x16x32_bf16 v[56:59], v[136:139], v[176:179], v[56:59]
	v_mfma_f32_16x16x32_bf16 v[44:47], v[128:131], v[184:187], v[44:47]
	v_mfma_f32_16x16x32_bf16 v[40:43], v[136:139], v[184:187], v[40:43]
	v_mfma_f32_16x16x32_bf16 v[28:31], v[128:131], v[192:195], v[28:31]
	v_mfma_f32_16x16x32_bf16 v[24:27], v[136:139], v[192:195], v[24:27]
	v_mfma_f32_16x16x32_bf16 v[12:15], v[128:131], v[200:203], v[12:15]
	v_mfma_f32_16x16x32_bf16 v[8:11], v[136:139], v[200:203], v[8:11]
	v_mfma_f32_16x16x32_bf16 v[60:63], v[132:135], v[180:183], v[60:63]
	v_mfma_f32_16x16x32_bf16 v[56:59], v[140:143], v[180:183], v[56:59]
	v_mfma_f32_16x16x32_bf16 v[44:47], v[132:135], v[188:191], v[44:47]
	v_mfma_f32_16x16x32_bf16 v[40:43], v[140:143], v[188:191], v[40:43]
	v_mfma_f32_16x16x32_bf16 v[28:31], v[132:135], v[196:199], v[28:31]
	v_mfma_f32_16x16x32_bf16 v[24:27], v[140:143], v[196:199], v[24:27]
	v_mfma_f32_16x16x32_bf16 v[12:15], v[132:135], v[204:207], v[12:15]
	v_mfma_f32_16x16x32_bf16 v[8:11], v[140:143], v[204:207], v[8:11]
	v_mfma_f32_16x16x32_bf16 v[52:55], v[156:159], v[176:179], v[52:55]
	v_mfma_f32_16x16x32_bf16 v[48:51], v[168:171], v[176:179], v[48:51]
	v_mfma_f32_16x16x32_bf16 v[36:39], v[156:159], v[184:187], v[36:39]
	v_mfma_f32_16x16x32_bf16 v[32:35], v[168:171], v[184:187], v[32:35]
	v_mfma_f32_16x16x32_bf16 v[20:23], v[156:159], v[192:195], v[20:23]
	v_mfma_f32_16x16x32_bf16 v[16:19], v[168:171], v[192:195], v[16:19]
	v_mfma_f32_16x16x32_bf16 v[4:7], v[156:159], v[200:203], v[4:7]
	v_mfma_f32_16x16x32_bf16 v[0:3], v[168:171], v[200:203], v[0:3]
	v_mfma_f32_16x16x32_bf16 v[52:55], v[164:167], v[180:183], v[52:55]
	v_mfma_f32_16x16x32_bf16 v[48:51], v[172:175], v[180:183], v[48:51]
	v_mfma_f32_16x16x32_bf16 v[36:39], v[164:167], v[188:191], v[36:39]
	v_mfma_f32_16x16x32_bf16 v[32:35], v[172:175], v[188:191], v[32:35]
	v_mfma_f32_16x16x32_bf16 v[20:23], v[164:167], v[196:199], v[20:23]
	v_mfma_f32_16x16x32_bf16 v[16:19], v[172:175], v[196:199], v[16:19]
	v_mfma_f32_16x16x32_bf16 v[4:7], v[164:167], v[204:207], v[4:7]
	v_mfma_f32_16x16x32_bf16 v[0:3], v[172:175], v[204:207], v[0:3]
	s_barrier
; #define PG8_STAGE(bufoff, gbase, voff) do { _Pragma("unroll") for (int _i = 0; _i < 2; ++_i) \
;         __builtin_amdgcn_global_load_lds((const unsigned*)((const char*)(gbase) + (voff)[_i]), (PG8_LAS unsigned*)(lds + (bufoff) + ldsw + _i * 8192), 16, 0, 0); } while (0)
; #define PG8_LDA(dst, b, h) do { _Pragma("unroll") for (int m = 0; m < 4; ++m) _Pragma("unroll") for (int k = 0; k < 2; ++k) dst[m][k] = *(const PG8_LAS bf16x8*)(lds + PG8_SA(b, h) + aoff + m * 2048 + k * 1024); } while (0)
; #define PG8_LDB(dst, b, h) do { _Pragma("unroll") for (int n = 0; n < 2; ++n) _Pragma("unroll") for (int k = 0; k < 2; ++k) dst[n][k] = *(const PG8_LAS bf16x8*)(lds + PG8_SB(b, h) + boff + n * 2048 + k * 1024); } while (0)
; #define PG8_MMA(ai, bj, At, Bt) do { __builtin_amdgcn_s_setprio(1); _Pragma("unroll") for (int m = 0; m < 4; ++m) _Pragma("unroll") for (int n = 0; n < 2; ++n) _Pragma("unroll") for (int k = 0; k < 2; ++k) \
;         acc[ai][bj][m][n] = __builtin_amdgcn_mfma_f32_16x16x32_bf16(Bt[n][k], At[m][k], acc[ai][bj][m][n], 0, 0, 0); __builtin_amdgcn_s_setprio(0); } while (0)
; #define PG8_WAIT_V(n) asm volatile("s_waitcnt vmcnt(" #n ")" ::: "memory")
; #define PG8_WAIT_L(n) asm volatile("s_waitcnt lgkmcnt(" #n ")" ::: "memory")
; #define PG8_BAR __builtin_amdgcn_s_barrier()
; #define PG8_SCHED __builtin_amdgcn_sched_barrier(0)
; template <class Epi, class Sched, bool ALIGN_EPI = false, bool SP2 = false>
; __device__ __forceinline__ void gemm_phase(PG8_LAS unsigned char* lds, const Gemm g, const Sched& S, const Epi& E) {
;     ...
;             PG8_LDB(B0, 1, 0); PG8_LDB(B1, 1, 1); PG8_SCHED; PG8_LDA(At, 1, 0); PG8_STAGE(PG8_SA(0, 1), a2 + hstep, voffA);
;             PG8_WAIT_V(8); PG8_WAIT_L(0); PG8_BAR; PG8_MMA(0, 0, At, B0); PG8_MMA(0, 1, At, B1); PG8_BAR; PG8_SCHED;
;             PG8_LDA(At, 1, 1); PG8_STAGE(PG8_SB(1, 0), b3, voffB); PG8_STAGE(PG8_SB(1, 1), b3 + hstep, voffB); PG8_STAGE(PG8_SA(1, 0), a3, voffA);
;             PG8_WAIT_V(8); PG8_WAIT_L(0); PG8_BAR; PG8_MMA(1, 0, At, B0); PG8_MMA(1, 1, At, B1); PG8_BAR; PG8_SCHED;
;     ...
;         if constexpr (ALIGN_EPI) { if (wr == 0) PG8_BAR; }
	s_add_i32 s69, 0, 0x18000
	s_add_i32 s70, 0, 0x1c000
	v_add_u32_e32 v140, s69, v162
	v_add_u32_e32 v160, s70, v162
	ds_read_b128 v[128:131], v140
	ds_read_b128 v[132:135], v140 offset:1024
	ds_read_b128 v[136:139], v140 offset:2048
	ds_read_b128 v[140:143], v140 offset:3072
	ds_read_b128 v[156:159], v160
	ds_read_b128 v[164:167], v160 offset:1024
	ds_read_b128 v[168:171], v160 offset:2048
	ds_read_b128 v[172:175], v160 offset:3072
	s_add_u32 s64, s64, 0x4000
	s_addc_u32 s65, s65, 0
	s_mov_b32 m0, s41
	ds_read_b128 v[176:179], v163 offset:32768
	ds_read_b128 v[180:183], v163 offset:33792
	ds_read_b128 v[184:187], v163 offset:34816
	ds_read_b128 v[188:191], v163 offset:35840
	ds_read_b128 v[192:195], v163 offset:36864
	ds_read_b128 v[196:199], v163 offset:37888
	ds_read_b128 v[200:203], v163 offset:38912
	ds_read_b128 v[204:207], v163 offset:39936
	global_load_lds_dwordx4 v150, s[64:65]
	s_mov_b32 m0, s42
	s_nop 0
	global_load_lds_dwordx4 v146, s[64:65]
	s_waitcnt vmcnt(8) lgkmcnt(0)
	s_barrier
	v_mfma_f32_16x16x32_bf16 v[124:127], v[128:131], v[176:179], v[124:127]
	v_mfma_f32_16x16x32_bf16 v[120:123], v[136:139], v[176:179], v[120:123]
	v_mfma_f32_16x16x32_bf16 v[108:111], v[128:131], v[184:187], v[108:111]
	v_mfma_f32_16x16x32_bf16 v[104:107], v[136:139], v[184:187], v[104:107]
	v_mfma_f32_16x16x32_bf16 v[92:95], v[128:131], v[192:195], v[92:95]
	v_mfma_f32_16x16x32_bf16 v[88:91], v[136:139], v[192:195], v[88:91]
	v_mfma_f32_16x16x32_bf16 v[76:79], v[128:131], v[200:203], v[76:79]
	v_mfma_f32_16x16x32_bf16 v[72:75], v[136:139], v[200:203], v[72:75]
	v_mfma_f32_16x16x32_bf16 v[124:127], v[132:135], v[180:183], v[124:127]
	v_mfma_f32_16x16x32_bf16 v[120:123], v[140:143], v[180:183], v[120:123]
	v_mfma_f32_16x16x32_bf16 v[108:111], v[132:135], v[188:191], v[108:111]
	v_mfma_f32_16x16x32_bf16 v[104:107], v[140:143], v[188:191], v[104:107]
	v_mfma_f32_16x16x32_bf16 v[92:95], v[132:135], v[196:199], v[92:95]
	v_mfma_f32_16x16x32_bf16 v[88:91], v[140:143], v[196:199], v[88:91]
	v_mfma_f32_16x16x32_bf16 v[76:79], v[132:135], v[204:207], v[76:79]
	v_mfma_f32_16x16x32_bf16 v[72:75], v[140:143], v[204:207], v[72:75]
	v_mfma_f32_16x16x32_bf16 v[116:119], v[156:159], v[176:179], v[116:119]
	v_mfma_f32_16x16x32_bf16 v[112:115], v[168:171], v[176:179], v[112:115]
	v_mfma_f32_16x16x32_bf16 v[100:103], v[156:159], v[184:187], v[100:103]
	v_mfma_f32_16x16x32_bf16 v[96:99], v[168:171], v[184:187], v[96:99]
	v_mfma_f32_16x16x32_bf16 v[84:87], v[156:159], v[192:195], v[84:87]
	v_mfma_f32_16x16x32_bf16 v[80:83], v[168:171], v[192:195], v[80:83]
	v_mfma_f32_16x16x32_bf16 v[68:71], v[156:159], v[200:203], v[68:71]
	v_mfma_f32_16x16x32_bf16 v[64:67], v[168:171], v[200:203], v[64:67]
	v_mfma_f32_16x16x32_bf16 v[116:119], v[164:167], v[180:183], v[116:119]
	v_mfma_f32_16x16x32_bf16 v[112:115], v[172:175], v[180:183], v[112:115]
	v_mfma_f32_16x16x32_bf16 v[100:103], v[164:167], v[188:191], v[100:103]
	v_mfma_f32_16x16x32_bf16 v[96:99], v[172:175], v[188:191], v[96:99]
	v_mfma_f32_16x16x32_bf16 v[84:87], v[164:167], v[196:199], v[84:87]
	v_mfma_f32_16x16x32_bf16 v[80:83], v[172:175], v[196:199], v[80:83]
	v_mfma_f32_16x16x32_bf16 v[68:71], v[164:167], v[204:207], v[68:71]
	v_mfma_f32_16x16x32_bf16 v[64:67], v[172:175], v[204:207], v[64:67]
	s_barrier
	s_add_u32 s64, s62, 0x8000
	s_addc_u32 s65, s63, 0
	s_add_i32 s69, s69, s30
	s_mov_b32 m0, s69
	ds_read_b128 v[176:179], v163 offset:49152
	ds_read_b128 v[180:183], v163 offset:50176
	ds_read_b128 v[184:187], v163 offset:51200
	ds_read_b128 v[188:191], v163 offset:52224
	ds_read_b128 v[192:195], v163 offset:53248
	ds_read_b128 v[196:199], v163 offset:54272
	ds_read_b128 v[200:203], v163 offset:55296
	ds_read_b128 v[204:207], v163 offset:56320
	global_load_lds_dwordx4 v148, s[64:65]
	s_add_i32 m0, s69, 0x2000
	s_add_u32 s62, s62, 0xc000
	v_lshl_add_u64 v[160:161], s[64:65], 0, v[144:145]
	s_addc_u32 s63, s63, 0
	s_add_i32 s64, s70, s30
	global_load_lds_dwordx4 v[160:161], off
	s_mov_b32 m0, s64
	s_nop 0
	global_load_lds_dwordx4 v148, s[62:63]
	s_add_i32 m0, s64, 0x2000
	s_nop 0
	global_load_lds_dwordx4 v144, s[62:63]
	s_mov_b32 m0, s54
	s_nop 0
	global_load_lds_dwordx4 v150, s[20:21]
	s_mov_b32 m0, s55
	s_nop 0
	global_load_lds_dwordx4 v146, s[20:21]
	s_waitcnt vmcnt(8) lgkmcnt(0)
	s_barrier
	v_mfma_f32_16x16x32_bf16 v[60:63], v[128:131], v[176:179], v[60:63]
	v_mfma_f32_16x16x32_bf16 v[56:59], v[136:139], v[176:179], v[56:59]
	v_mfma_f32_16x16x32_bf16 v[44:47], v[128:131], v[184:187], v[44:47]
	v_mfma_f32_16x16x32_bf16 v[40:43], v[136:139], v[184:187], v[40:43]
	v_mfma_f32_16x16x32_bf16 v[28:31], v[128:131], v[192:195], v[28:31]
	v_mfma_f32_16x16x32_bf16 v[24:27], v[136:139], v[192:195], v[24:27]
	v_mfma_f32_16x16x32_bf16 v[12:15], v[128:131], v[200:203], v[12:15]
	v_mfma_f32_16x16x32_bf16 v[8:11], v[136:139], v[200:203], v[8:11]
	v_mfma_f32_16x16x32_bf16 v[60:63], v[132:135], v[180:183], v[60:63]
	v_mfma_f32_16x16x32_bf16 v[56:59], v[140:143], v[180:183], v[56:59]
	v_mfma_f32_16x16x32_bf16 v[44:47], v[132:135], v[188:191], v[44:47]
	v_mfma_f32_16x16x32_bf16 v[40:43], v[140:143], v[188:191], v[40:43]
	v_mfma_f32_16x16x32_bf16 v[28:31], v[132:135], v[196:199], v[28:31]
	v_mfma_f32_16x16x32_bf16 v[24:27], v[140:143], v[196:199], v[24:27]
	v_mfma_f32_16x16x32_bf16 v[12:15], v[132:135], v[204:207], v[12:15]
	v_mfma_f32_16x16x32_bf16 v[8:11], v[140:143], v[204:207], v[8:11]
	v_mfma_f32_16x16x32_bf16 v[52:55], v[156:159], v[176:179], v[52:55]
	v_mfma_f32_16x16x32_bf16 v[48:51], v[168:171], v[176:179], v[48:51]
	v_mfma_f32_16x16x32_bf16 v[36:39], v[156:159], v[184:187], v[36:39]
	v_mfma_f32_16x16x32_bf16 v[32:35], v[168:171], v[184:187], v[32:35]
	v_mfma_f32_16x16x32_bf16 v[20:23], v[156:159], v[192:195], v[20:23]
	v_mfma_f32_16x16x32_bf16 v[16:19], v[168:171], v[192:195], v[16:19]
	v_mfma_f32_16x16x32_bf16 v[4:7], v[156:159], v[200:203], v[4:7]
	v_mfma_f32_16x16x32_bf16 v[0:3], v[168:171], v[200:203], v[0:3]
	v_mfma_f32_16x16x32_bf16 v[52:55], v[164:167], v[180:183], v[52:55]
	v_mfma_f32_16x16x32_bf16 v[48:51], v[172:175], v[180:183], v[48:51]
	v_mfma_f32_16x16x32_bf16 v[36:39], v[164:167], v[188:191], v[36:39]
	v_mfma_f32_16x16x32_bf16 v[32:35], v[172:175], v[188:191], v[32:35]
	v_mfma_f32_16x16x32_bf16 v[20:23], v[164:167], v[196:199], v[20:23]
	v_mfma_f32_16x16x32_bf16 v[16:19], v[172:175], v[196:199], v[16:19]
	v_mfma_f32_16x16x32_bf16 v[4:7], v[164:167], v[204:207], v[4:7]
	v_mfma_f32_16x16x32_bf16 v[0:3], v[172:175], v[204:207], v[0:3]
	s_barrier
	s_add_i32 s68, s68, 2
	s_add_u32 s18, s18, 0x10000
	s_addc_u32 s19, s19, 0
	s_add_u32 s66, s66, 0x10000
	s_addc_u32 s67, s67, 0
	s_cmp_gt_u32 s68, 13
	s_cbranch_scc0 .LBB0_1356
	s_andn2_b64 vcc, s[6:7], s[2:3]
	s_cbranch_vccz .LBB0_1359
	s_barrier
; __device__ __forceinline__ float rstd_from_quarter(const v4f a, int ln) {
;     float s = (a.x + a.y) + (a.z + a.w);
;     s += __int_as_float(__builtin_amdgcn_ds_bpermute((ln ^ 16) << 2, __float_as_int(s))); s += __int_as_float(__builtin_amdgcn_ds_bpermute((ln ^ 32) << 2, __float_as_int(s)));
;     return rsqrtf(s * (1.0f / DM) + EPS);
; }
; __device__ __forceinline__ float row_rstd4(const float* ssp, int row, int fq, int ln) {
;     const v4f a = *(const v4f*)(ssp + (size_t)row * 16 + 4 * fq);
;     float s = (a.x + a.y) + (a.z + a.w);
;     s += __int_as_float(__builtin_amdgcn_ds_bpermute((ln ^ 16) << 2, __float_as_int(s))); s += __int_as_float(__builtin_amdgcn_ds_bpermute((ln ^ 32) << 2, __float_as_int(s)));
;     return rsqrtf(s * (1.0f / DM) + EPS);
; }
; __device__ __forceinline__ float row_rstd(const float* ssp, int row) {
;     const v4f* p = (const v4f*)(ssp + (size_t)row * 16);
;     const v4f a = p[0], b = p[1], c = p[2], d = p[3];
;     const float s = ((a.x + a.y) + (a.z + a.w)) + ((b.x + b.y) + (b.z + b.w)) + ((c.x + c.y) + (c.z + c.w)) + ((d.x + d.y) + (d.z + d.w));
;     return rsqrtf(s * (1.0f / DM) + EPS);
;     __device__ __forceinline__ void operator()(const f32x4 (&acc)[2][2][4][2], const Unit& u, int wr, int wc, int, int) const {
;         int t_ = threadIdx.x; asm volatile("" : "+v"(t_)); const int fr = t_ & 15, fq = (t_ >> 4) & 3;
;         const int row0 = u.pm * BM + wr * 64 + fr, col0 = u.pn * HALF + wc * 32 + 8 * fq;
;         v4f pq[2][4];
; #pragma unroll
;         for (int ai = 0; ai < 2; ++ai)
; #pragma unroll
;             for (int m = 0; m < 4; ++m) pq[ai][m] = *(const v4f*)(ssp + (size_t)(row0 + ai * HALF + m * 16) * 16 + 4 * fq);
;         asm volatile("" ::: "memory");
; #pragma unroll
;         for (int ai = 0; ai < 2; ++ai)
; #pragma unroll
;             for (int m = 0; m < 4; ++m) {
;                 const int row = row0 + ai * HALF + m * 16; const float rs = rstd_from_quarter(pq[ai][m], fq * 16 + fr);
;                 float h[8];
; #pragma unroll
;                 for (int n = 0; n < 2; ++n) { const f32x4 g = acc[ai][0][m][n] * rs, uu = acc[ai][1][m][n] * rs; const f32x4 hv = (g * sigmoid4(g)) * uu;
;                     h[n * 4 + 0] = hv[0]; h[n * 4 + 1] = hv[1]; h[n * 4 + 2] = hv[2]; h[n * 4 + 3] = hv[3]; }
;                 __builtin_nontemporal_store(pack8(h), (u32x4*)(O + tl(row, col0, FF)));
;             }
.LBB0_1359:
	s_lshl_b32 s9, s16, 8
	v_mov_b32_e32 v142, v230
	s_add_i32 s9, s9, s52
	s_mov_b32 s16, 0x358637bd
	v_and_or_b32 v136, v142, 15, s9
	v_bfe_u32 v143, v142, 4, 2
	v_or_b32_e32 v132, 16, v136
	v_lshlrev_b32_e32 v220, 4, v143
	v_ashrrev_i32_e32 v137, 31, v136
	v_ashrrev_i32_e32 v133, 31, v132
	v_lshl_add_u64 v[138:139], s[4:5], 0, v[220:221]
	v_lshlrev_b64 v[128:129], 6, v[136:137]
	v_lshlrev_b64 v[132:133], 6, v[132:133]
	v_lshl_add_u64 v[140:141], v[138:139], 0, v[128:129]
	v_lshl_add_u64 v[132:133], v[138:139], 0, v[132:133]
	global_load_dwordx4 v[128:131], v[140:141], off
	v_lshlrev_b32_e32 v137, 2, v142
	global_load_dwordx4 v[132:135], v[132:133], off
	v_or_b32_e32 v142, 32, v136
	v_or_b32_e32 v160, 48, v136
	v_add_u32_e32 v158, 0x80, v136
	v_lshl_or_b32 v166, v143, 3, s56
	v_lshlrev_b32_e32 v136, 6, v136
	v_ashrrev_i32_e32 v143, 31, v142
	v_bitop3_b32 v165, v137, 64, v244 bitop3:0x6c
	v_bitop3_b32 v164, v137, s90, v244 bitop3:0x6c
	v_ashrrev_i32_e32 v161, 31, v160
	v_and_or_b32 v167, v136, s84, v166
	v_lshlrev_b64 v[136:137], 6, v[142:143]
	v_lshlrev_b64 v[142:143], 6, v[160:161]
	v_lshl_add_u64 v[136:137], v[138:139], 0, v[136:137]
	v_lshl_add_u64 v[142:143], v[138:139], 0, v[142:143]
	global_load_dwordx4 v[168:171], v[136:137], off
	global_load_dwordx4 v[172:175], v[142:143], off
	v_ashrrev_i32_e32 v159, 31, v158
	v_lshlrev_b64 v[160:161], 6, v[158:159]
	v_lshl_add_u64 v[138:139], v[138:139], 0, v[160:161]
	s_lshl_b32 s11, s17, 7
	v_mov_b64_e32 v[156:157], s[16:17]
	s_or_b32 s11, s11, s53
	s_ashr_i32 s16, s11, 6
	s_ashr_i32 s17, s16, 31
	s_ashr_i32 s9, s9, 8
	s_lshl_b64 s[16:17], s[16:17], 15
	s_add_u32 s16, s50, s16
	v_lshlrev_b32_e32 v220, 1, v167
	s_addc_u32 s17, s51, s17
	v_lshl_add_u64 v[176:177], s[16:17], 0, v[220:221]
	s_waitcnt vmcnt(0)
	v_mov_b32_e32 v160, v129
	v_mov_b32_e32 v161, v130
	v_mov_b32_e32 v129, v131
	v_mov_b32_e32 v130, v133
	v_mov_b32_e32 v131, v134
	v_mov_b32_e32 v133, v135
	v_pk_add_f32 v[128:129], v[160:161], v[128:129]
	v_pk_add_f32 v[130:131], v[130:131], v[132:133]
	v_mov_b32_e32 v133, v128
	v_mov_b32_e32 v132, v130
	v_mov_b32_e32 v128, v131
	v_pk_add_f32 v[128:129], v[132:133], v[128:129]
	ds_bpermute_b32 v131, v165, v129
	ds_bpermute_b32 v130, v165, v128
	v_add_co_u32_e32 v160, vcc, s80, v140
	s_waitcnt lgkmcnt(0)
	v_pk_add_f32 v[178:179], v[128:129], v[130:131]
	ds_bpermute_b32 v181, v164, v179
	ds_bpermute_b32 v180, v164, v178
	v_addc_co_u32_e32 v161, vcc, 0, v141, vcc
	global_load_dwordx4 v[140:143], v[138:139], off
	s_nop 0
	global_load_dwordx4 v[136:139], v[160:161], off offset:1024
	global_load_dwordx4 v[132:135], v[160:161], off offset:2048
	global_load_dwordx4 v[128:131], v[160:161], off offset:3072
	s_waitcnt lgkmcnt(0)
	v_pk_add_f32 v[160:161], v[178:179], v[180:181]
	s_nop 0
	v_pk_fma_f32 v[178:179], v[160:161], s[74:75], v[156:157] op_sel_hi:[1,0,0]
	v_mad_i64_i32 v[160:161], s[18:19], s9, v245, v[176:177]
	v_mul_f32_e32 v159, 0x4b800000, v179
	v_cmp_gt_f32_e32 vcc, s25, v179
	v_mul_f32_e32 v167, 0x4b800000, v178
	s_nop 0
	v_cndmask_b32_e32 v159, v179, v159, vcc
	v_rsq_f32_e32 v159, v159
	s_nop 0
	v_mul_f32_e32 v176, 0x45800000, v159
	v_cndmask_b32_e32 v176, v159, v176, vcc
	v_pk_mul_f32 v[120:121], v[120:121], v[176:177] op_sel_hi:[1,0]
	v_pk_mul_f32 v[122:123], v[122:123], v[176:177] op_sel_hi:[1,0]
	v_pk_mul_f32 v[184:185], v[120:121], s[38:39] op_sel_hi:[1,0]
	v_pk_mul_f32 v[182:183], v[122:123], s[38:39] op_sel_hi:[1,0]
	v_exp_f32_e32 v184, v184
	v_exp_f32_e32 v182, v182
	v_exp_f32_e32 v183, v183
	v_exp_f32_e32 v185, v185
	v_pk_mul_f32 v[124:125], v[124:125], v[176:177] op_sel_hi:[1,0]
	v_pk_mul_f32 v[126:127], v[126:127], v[176:177] op_sel_hi:[1,0]
	v_pk_mul_f32 v[180:181], v[124:125], s[38:39] op_sel_hi:[1,0]
	v_pk_add_f32 v[182:183], v[182:183], 1.0 op_sel_hi:[1,0]
	v_pk_add_f32 v[184:185], v[184:185], 1.0 op_sel_hi:[1,0]
	v_exp_f32_e32 v180, v180
	v_exp_f32_e32 v181, v181
	v_rcp_f32_e32 v184, v184
	v_rcp_f32_e32 v185, v185
	v_rcp_f32_e32 v182, v182
	v_rcp_f32_e32 v183, v183
	v_pk_mul_f32 v[116:117], v[116:117], v[176:177] op_sel_hi:[1,0]
	v_pk_mul_f32 v[118:119], v[118:119], v[176:177] op_sel_hi:[1,0]
	v_pk_mul_f32 v[112:113], v[112:113], v[176:177] op_sel_hi:[1,0]
	v_pk_mul_f32 v[114:115], v[114:115], v[176:177] op_sel_hi:[1,0]
	v_pk_mul_f32 v[176:177], v[126:127], s[38:39] op_sel_hi:[1,0]
	v_pk_add_f32 v[180:181], v[180:181], 1.0 op_sel_hi:[1,0]
	v_exp_f32_e32 v176, v176
	v_exp_f32_e32 v177, v177
	v_pk_mul_f32 v[120:121], v[120:121], v[184:185]
	v_pk_mul_f32 v[122:123], v[122:123], v[182:183]
	v_cmp_gt_f32_e32 vcc, s25, v178
	v_rcp_f32_e32 v180, v180
	v_rcp_f32_e32 v181, v181
	v_pk_mul_f32 v[122:123], v[114:115], v[122:123]
	v_pk_mul_f32 v[114:115], v[112:113], v[120:121]
	v_cndmask_b32_e32 v112, v178, v167, vcc
	v_pk_add_f32 v[176:177], v[176:177], 1.0 op_sel_hi:[1,0]
	v_rsq_f32_e32 v120, v112
	v_rcp_f32_e32 v176, v176
	v_rcp_f32_e32 v177, v177
	v_pk_mul_f32 v[124:125], v[124:125], v[180:181]
	v_cvt_pk_bf16_f32 v114, v114, v115
	v_pk_mul_f32 v[116:117], v[116:117], v[124:125]
	v_mul_f32_e32 v115, 0x45800000, v120
	v_pk_mul_f32 v[126:127], v[126:127], v[176:177]
	v_cvt_pk_bf16_f32 v112, v116, v117
	v_cndmask_b32_e32 v116, v120, v115, vcc
	v_pk_mul_f32 v[118:119], v[118:119], v[126:127]
	v_pk_mul_f32 v[108:109], v[108:109], v[116:117] op_sel_hi:[1,0]
	v_pk_mul_f32 v[110:111], v[110:111], v[116:117] op_sel_hi:[1,0]
	v_cvt_pk_bf16_f32 v113, v118, v119
	v_pk_mul_f32 v[118:119], v[110:111], s[38:39] op_sel_hi:[1,0]
	v_pk_mul_f32 v[120:121], v[108:109], s[38:39] op_sel_hi:[1,0]
	v_exp_f32_e32 v118, v118
	v_exp_f32_e32 v120, v120
	v_exp_f32_e32 v119, v119
	v_exp_f32_e32 v121, v121
; __device__ __forceinline__ v4u pack8(const float* x) { v4u o; o.x = pk2(x[0], x[1]); o.y = pk2(x[2], x[3]); o.z = pk2(x[4], x[5]); o.w = pk2(x[6], x[7]); return o; }
; __device__ __forceinline__ size_t tl(int row, int col, int K) { return (size_t)(row >> 8) * ((size_t)256 * K) + (size_t)(col >> 6) * (256 * 64) + (size_t)((row & 255) * 64 + (col & 63)); }
; __device__ __forceinline__ f32x4 sigmoid4(f32x4 x) {
;     const f32x4 z = x * (-1.4426950408889634f); f32x4 e;
;     e[0] = __builtin_amdgcn_exp2f(z[0]); e[1] = __builtin_amdgcn_exp2f(z[1]); e[2] = __builtin_amdgcn_exp2f(z[2]); e[3] = __builtin_amdgcn_exp2f(z[3]);
;     const f32x4 d = e + 1.0f; f32x4 r;
;     r[0] = __builtin_amdgcn_rcpf(d[0]); r[1] = __builtin_amdgcn_rcpf(d[1]); r[2] = __builtin_amdgcn_rcpf(d[2]); r[3] = __builtin_amdgcn_rcpf(d[3]);
;     return r;
; }
;     __device__ __forceinline__ void operator()(const f32x4 (&acc)[2][2][4][2], const Unit& u, int wr, int wc, int, int) const {
;     ...
;             for (int m = 0; m < 4; ++m) {
;                 const int row = row0 + ai * HALF + m * 16; const float rs = rstd_from_quarter(pq[ai][m], fq * 16 + fr);
;                 float h[8];
; #pragma unroll
;                 for (int n = 0; n < 2; ++n) { const f32x4 g = acc[ai][0][m][n] * rs, uu = acc[ai][1][m][n] * rs; const f32x4 hv = (g * sigmoid4(g)) * uu;
;                     h[n * 4 + 0] = hv[0]; h[n * 4 + 1] = hv[1]; h[n * 4 + 2] = hv[2]; h[n * 4 + 3] = hv[3]; }
;                 __builtin_nontemporal_store(pack8(h), (u32x4*)(O + tl(row, col0, FF)));
;             }
	v_cvt_pk_bf16_f32 v115, v122, v123
	global_store_dwordx4 v[160:161], v[112:115], off nt
	v_pk_mul_f32 v[100:101], v[100:101], v[116:117] op_sel_hi:[1,0]
	v_pk_mul_f32 v[102:103], v[102:103], v[116:117] op_sel_hi:[1,0]
	v_pk_add_f32 v[112:113], v[118:119], 1.0 op_sel_hi:[1,0]
	v_pk_add_f32 v[114:115], v[120:121], 1.0 op_sel_hi:[1,0]
	v_rcp_f32_e32 v112, v112
	v_rcp_f32_e32 v114, v114
	v_rcp_f32_e32 v115, v115
	v_rcp_f32_e32 v113, v113
	v_pk_mul_f32 v[104:105], v[104:105], v[116:117] op_sel_hi:[1,0]
	v_pk_mul_f32 v[106:107], v[106:107], v[116:117] op_sel_hi:[1,0]
	v_pk_mul_f32 v[108:109], v[108:109], v[114:115]
	v_pk_mul_f32 v[110:111], v[110:111], v[112:113]
	v_mov_b32_e32 v112, v169
	v_mov_b32_e32 v113, v170
	v_mov_b32_e32 v169, v171
	v_mov_b32_e32 v114, v173
	v_mov_b32_e32 v115, v174
	v_mov_b32_e32 v173, v175
	v_pk_add_f32 v[112:113], v[112:113], v[168:169]
	v_pk_add_f32 v[114:115], v[114:115], v[172:173]
	v_pk_mul_f32 v[96:97], v[96:97], v[116:117] op_sel_hi:[1,0]
	v_pk_mul_f32 v[98:99], v[98:99], v[116:117] op_sel_hi:[1,0]
	v_mov_b32_e32 v116, v114
	v_mov_b32_e32 v117, v112
	v_mov_b32_e32 v112, v115
	v_pk_add_f32 v[112:113], v[116:117], v[112:113]
	v_pk_mul_f32 v[102:103], v[102:103], v[110:111]
	v_pk_mul_f32 v[100:101], v[100:101], v[108:109]
	v_pk_mul_f32 v[108:109], v[106:107], s[38:39] op_sel_hi:[1,0]
	v_pk_mul_f32 v[110:111], v[104:105], s[38:39] op_sel_hi:[1,0]
	ds_bpermute_b32 v115, v165, v113
	ds_bpermute_b32 v114, v165, v112
	v_exp_f32_e32 v110, v110
	v_exp_f32_e32 v108, v108
	v_exp_f32_e32 v109, v109
	v_exp_f32_e32 v111, v111
	s_waitcnt lgkmcnt(0)
	v_pk_add_f32 v[112:113], v[112:113], v[114:115]
	ds_bpermute_b32 v115, v164, v113
	v_pk_add_f32 v[108:109], v[108:109], 1.0 op_sel_hi:[1,0]
	v_pk_add_f32 v[110:111], v[110:111], 1.0 op_sel_hi:[1,0]
	v_rcp_f32_e32 v108, v108
	v_rcp_f32_e32 v110, v110
	v_rcp_f32_e32 v111, v111
	v_rcp_f32_e32 v109, v109
	ds_bpermute_b32 v114, v164, v112
	v_pk_mul_f32 v[104:105], v[104:105], v[110:111]
	v_pk_mul_f32 v[106:107], v[106:107], v[108:109]
	s_nop 0
	v_pk_mul_f32 v[106:107], v[98:99], v[106:107]
	v_pk_mul_f32 v[98:99], v[96:97], v[104:105]
	s_waitcnt lgkmcnt(0)
	v_pk_add_f32 v[96:97], v[112:113], v[114:115]
	v_cvt_pk_bf16_f32 v98, v98, v99
	v_pk_fma_f32 v[104:105], v[96:97], s[74:75], v[156:157] op_sel_hi:[1,0,0]
	v_cvt_pk_bf16_f32 v97, v102, v103
	v_mul_f32_e32 v96, 0x4b800000, v105
	v_cmp_gt_f32_e32 vcc, s25, v105
	s_nop 1
	v_cndmask_b32_e32 v96, v105, v96, vcc
	v_rsq_f32_e32 v105, v96
	v_cvt_pk_bf16_f32 v96, v100, v101
	v_mul_f32_e32 v99, 0x45800000, v105
	v_cndmask_b32_e32 v100, v105, v99, vcc
	v_pk_mul_f32 v[92:93], v[92:93], v[100:101] op_sel_hi:[1,0]
	v_pk_mul_f32 v[94:95], v[94:95], v[100:101] op_sel_hi:[1,0]
	v_pk_mul_f32 v[108:109], v[92:93], s[38:39] op_sel_hi:[1,0]
	v_pk_mul_f32 v[102:103], v[94:95], s[38:39] op_sel_hi:[1,0]
	v_exp_f32_e32 v108, v108
	v_exp_f32_e32 v102, v102
	v_exp_f32_e32 v103, v103
	v_exp_f32_e32 v109, v109
	v_cvt_pk_bf16_f32 v99, v106, v107
	global_store_dwordx4 v[160:161], v[96:99], off offset:2048 nt
	v_pk_mul_f32 v[88:89], v[88:89], v[100:101] op_sel_hi:[1,0]
	v_pk_mul_f32 v[90:91], v[90:91], v[100:101] op_sel_hi:[1,0]
	v_pk_add_f32 v[96:97], v[102:103], 1.0 op_sel_hi:[1,0]
	v_pk_add_f32 v[98:99], v[108:109], 1.0 op_sel_hi:[1,0]
	v_rcp_f32_e32 v96, v96
	v_rcp_f32_e32 v98, v98
	v_rcp_f32_e32 v99, v99
	v_rcp_f32_e32 v97, v97
	v_pk_mul_f32 v[84:85], v[84:85], v[100:101] op_sel_hi:[1,0]
	v_pk_mul_f32 v[86:87], v[86:87], v[100:101] op_sel_hi:[1,0]
	v_pk_mul_f32 v[92:93], v[92:93], v[98:99]
	v_pk_mul_f32 v[94:95], v[94:95], v[96:97]
	v_pk_mul_f32 v[96:97], v[90:91], s[38:39] op_sel_hi:[1,0]
	v_pk_mul_f32 v[98:99], v[88:89], s[38:39] op_sel_hi:[1,0]
	v_exp_f32_e32 v96, v96
	v_exp_f32_e32 v98, v98
	v_exp_f32_e32 v97, v97
	v_exp_f32_e32 v99, v99
	v_pk_mul_f32 v[86:87], v[86:87], v[94:95]
	v_pk_mul_f32 v[84:85], v[84:85], v[92:93]
	v_pk_add_f32 v[92:93], v[96:97], 1.0 op_sel_hi:[1,0]
	v_pk_add_f32 v[94:95], v[98:99], 1.0 op_sel_hi:[1,0]
	v_rcp_f32_e32 v92, v92
	v_rcp_f32_e32 v94, v94
	v_rcp_f32_e32 v95, v95
	v_rcp_f32_e32 v93, v93
	v_pk_mul_f32 v[80:81], v[80:81], v[100:101] op_sel_hi:[1,0]
	v_pk_mul_f32 v[82:83], v[82:83], v[100:101] op_sel_hi:[1,0]
	v_pk_mul_f32 v[88:89], v[88:89], v[94:95]
	v_pk_mul_f32 v[90:91], v[90:91], v[92:93]
	v_cmp_gt_f32_e32 vcc, s25, v104
	v_pk_mul_f32 v[90:91], v[82:83], v[90:91]
	v_pk_mul_f32 v[82:83], v[80:81], v[88:89]
	v_mul_f32_e32 v81, 0x4b800000, v104
	v_cndmask_b32_e32 v81, v104, v81, vcc
	v_cvt_pk_bf16_f32 v80, v84, v85
	v_rsq_f32_e32 v84, v81
	v_cvt_pk_bf16_f32 v81, v86, v87
	v_cvt_pk_bf16_f32 v82, v82, v83
	v_cvt_pk_bf16_f32 v83, v90, v91
	v_mul_f32_e32 v85, 0x45800000, v84
	v_cndmask_b32_e32 v84, v84, v85, vcc
	v_pk_mul_f32 v[76:77], v[76:77], v[84:85] op_sel_hi:[1,0]
	v_pk_mul_f32 v[78:79], v[78:79], v[84:85] op_sel_hi:[1,0]
	v_pk_mul_f32 v[88:89], v[76:77], s[38:39] op_sel_hi:[1,0]
	v_pk_mul_f32 v[86:87], v[78:79], s[38:39] op_sel_hi:[1,0]
	v_exp_f32_e32 v88, v88
	v_exp_f32_e32 v89, v89
	v_exp_f32_e32 v86, v86
	v_exp_f32_e32 v87, v87
	v_add_co_u32_e32 v90, vcc, s85, v160
	v_pk_mul_f32 v[72:73], v[72:73], v[84:85] op_sel_hi:[1,0]
	s_nop 0
	v_addc_co_u32_e32 v91, vcc, 0, v161, vcc
	global_store_dwordx4 v[90:91], v[80:83], off nt
	v_pk_mul_f32 v[74:75], v[74:75], v[84:85] op_sel_hi:[1,0]
	v_pk_mul_f32 v[68:69], v[68:69], v[84:85] op_sel_hi:[1,0]
	v_pk_add_f32 v[80:81], v[86:87], 1.0 op_sel_hi:[1,0]
	v_pk_add_f32 v[82:83], v[88:89], 1.0 op_sel_hi:[1,0]
	v_rcp_f32_e32 v80, v80
	v_rcp_f32_e32 v82, v82
	v_rcp_f32_e32 v83, v83
	v_rcp_f32_e32 v81, v81
	v_pk_mul_f32 v[70:71], v[70:71], v[84:85] op_sel_hi:[1,0]
	v_pk_mul_f32 v[64:65], v[64:65], v[84:85] op_sel_hi:[1,0]
	v_pk_mul_f32 v[76:77], v[76:77], v[82:83]
	v_pk_mul_f32 v[78:79], v[78:79], v[80:81]
	v_pk_mul_f32 v[80:81], v[74:75], s[38:39] op_sel_hi:[1,0]
	v_pk_mul_f32 v[82:83], v[72:73], s[38:39] op_sel_hi:[1,0]
	v_exp_f32_e32 v80, v80
	v_exp_f32_e32 v82, v82
	v_exp_f32_e32 v81, v81
	v_exp_f32_e32 v83, v83
	v_pk_mul_f32 v[70:71], v[70:71], v[78:79]
	v_pk_mul_f32 v[68:69], v[68:69], v[76:77]
	v_pk_add_f32 v[76:77], v[80:81], 1.0 op_sel_hi:[1,0]
	v_pk_add_f32 v[78:79], v[82:83], 1.0 op_sel_hi:[1,0]
	v_rcp_f32_e32 v76, v76
	v_rcp_f32_e32 v78, v78
	v_rcp_f32_e32 v79, v79
	v_rcp_f32_e32 v77, v77
	v_pk_mul_f32 v[66:67], v[66:67], v[84:85] op_sel_hi:[1,0]
	v_pk_mul_f32 v[72:73], v[72:73], v[78:79]
	v_pk_mul_f32 v[74:75], v[74:75], v[76:77]
	s_nop 0
	v_pk_mul_f32 v[74:75], v[66:67], v[74:75]
	v_pk_mul_f32 v[66:67], v[64:65], v[72:73]
	s_waitcnt vmcnt(6)
; __device__ __forceinline__ v4u pack8(const float* x) { v4u o; o.x = pk2(x[0], x[1]); o.y = pk2(x[2], x[3]); o.z = pk2(x[4], x[5]); o.w = pk2(x[6], x[7]); return o; }
; __device__ __forceinline__ size_t tl(int row, int col, int K) { return (size_t)(row >> 8) * ((size_t)256 * K) + (size_t)(col >> 6) * (256 * 64) + (size_t)((row & 255) * 64 + (col & 63)); }
; __device__ __forceinline__ f32x4 sigmoid4(f32x4 x) {
;     const f32x4 z = x * (-1.4426950408889634f); f32x4 e;
;     e[0] = __builtin_amdgcn_exp2f(z[0]); e[1] = __builtin_amdgcn_exp2f(z[1]); e[2] = __builtin_amdgcn_exp2f(z[2]); e[3] = __builtin_amdgcn_exp2f(z[3]);
;     const f32x4 d = e + 1.0f; f32x4 r;
;     r[0] = __builtin_amdgcn_rcpf(d[0]); r[1] = __builtin_amdgcn_rcpf(d[1]); r[2] = __builtin_amdgcn_rcpf(d[2]); r[3] = __builtin_amdgcn_rcpf(d[3]);
;     return r;
; }
;     __device__ __forceinline__ void operator()(const f32x4 (&acc)[2][2][4][2], const Unit& u, int wr, int wc, int, int) const {
;     ...
;             for (int m = 0; m < 4; ++m) {
;                 const int row = row0 + ai * HALF + m * 16; const float rs = rstd_from_quarter(pq[ai][m], fq * 16 + fr);
;                 float h[8];
; #pragma unroll
;                 for (int n = 0; n < 2; ++n) { const f32x4 g = acc[ai][0][m][n] * rs, uu = acc[ai][1][m][n] * rs; const f32x4 hv = (g * sigmoid4(g)) * uu;
;                     h[n * 4 + 0] = hv[0]; h[n * 4 + 1] = hv[1]; h[n * 4 + 2] = hv[2]; h[n * 4 + 3] = hv[3]; }
;                 __builtin_nontemporal_store(pack8(h), (u32x4*)(O + tl(row, col0, FF)));
;             }
	v_mov_b32_e32 v64, v141
	v_mov_b32_e32 v65, v142
	v_mov_b32_e32 v141, v143
	s_waitcnt vmcnt(5)
	v_mov_b32_e32 v72, v137
	v_mov_b32_e32 v73, v138
	v_mov_b32_e32 v137, v139
	v_pk_add_f32 v[64:65], v[64:65], v[140:141]
	v_pk_add_f32 v[72:73], v[72:73], v[136:137]
	v_mov_b32_e32 v77, v64
	v_mov_b32_e32 v76, v72
	v_mov_b32_e32 v64, v73
	v_pk_add_f32 v[72:73], v[76:77], v[64:65]
	ds_bpermute_b32 v77, v165, v73
	ds_bpermute_b32 v76, v165, v72
	v_cvt_pk_bf16_f32 v64, v68, v69
	v_cvt_pk_bf16_f32 v65, v70, v71
	v_cvt_pk_bf16_f32 v66, v66, v67
	v_cvt_pk_bf16_f32 v67, v74, v75
	s_waitcnt lgkmcnt(0)
	v_pk_add_f32 v[68:69], v[72:73], v[76:77]
	ds_bpermute_b32 v71, v164, v69
	ds_bpermute_b32 v70, v164, v68
	global_store_dwordx4 v[90:91], v[64:67], off offset:2048 nt
	s_nop 1
	v_lshlrev_b32_e32 v64, 6, v158
	v_and_or_b32 v72, v64, s84, v166
	s_waitcnt lgkmcnt(0)
	v_pk_add_f32 v[64:65], v[68:69], v[70:71]
	v_lshlrev_b32_e32 v220, 1, v72
	v_pk_fma_f32 v[64:65], v[64:65], s[74:75], v[156:157] op_sel_hi:[1,0,0]
	v_lshrrev_b32_e32 v66, 8, v158
	v_mul_f32_e32 v67, 0x4b800000, v65
	v_cmp_gt_f32_e32 vcc, s25, v65
	s_nop 1
	v_cndmask_b32_e32 v65, v65, v67, vcc
	v_rsq_f32_e32 v65, v65
	v_mul_hi_i32_i24_e32 v67, 0x160000, v66
	v_mul_i32_i24_e32 v66, 0x160000, v66
	v_mul_f32_e32 v68, 0x45800000, v65
	v_cndmask_b32_e32 v68, v65, v68, vcc
	v_pk_mul_f32 v[70:71], v[60:61], v[68:69] op_sel_hi:[1,0]
	v_pk_mul_f32 v[62:63], v[62:63], v[68:69] op_sel_hi:[1,0]
	v_pk_mul_f32 v[72:73], v[70:71], s[38:39] op_sel_hi:[1,0]
	v_pk_mul_f32 v[60:61], v[62:63], s[38:39] op_sel_hi:[1,0]
	v_exp_f32_e32 v72, v72
	v_exp_f32_e32 v74, v60
	v_exp_f32_e32 v75, v61
	v_exp_f32_e32 v73, v73
	v_lshl_add_u64 v[60:61], s[16:17], 0, v[220:221]
	v_lshl_add_u64 v[60:61], v[60:61], 0, v[66:67]
	v_pk_add_f32 v[66:67], v[74:75], 1.0 op_sel_hi:[1,0]
	v_pk_add_f32 v[72:73], v[72:73], 1.0 op_sel_hi:[1,0]
	v_rcp_f32_e32 v66, v66
	v_rcp_f32_e32 v72, v72
	v_rcp_f32_e32 v73, v73
	v_rcp_f32_e32 v67, v67
	v_pk_mul_f32 v[56:57], v[56:57], v[68:69] op_sel_hi:[1,0]
	v_pk_mul_f32 v[58:59], v[58:59], v[68:69] op_sel_hi:[1,0]
	v_pk_mul_f32 v[70:71], v[70:71], v[72:73]
	v_pk_mul_f32 v[62:63], v[62:63], v[66:67]
	v_pk_mul_f32 v[66:67], v[58:59], s[38:39] op_sel_hi:[1,0]
	v_pk_mul_f32 v[72:73], v[56:57], s[38:39] op_sel_hi:[1,0]
	v_exp_f32_e32 v66, v66
	v_exp_f32_e32 v72, v72
	v_exp_f32_e32 v67, v67
	v_exp_f32_e32 v73, v73
	v_pk_mul_f32 v[54:55], v[54:55], v[68:69] op_sel_hi:[1,0]
	v_pk_mul_f32 v[48:49], v[48:49], v[68:69] op_sel_hi:[1,0]
	v_pk_mul_f32 v[54:55], v[54:55], v[62:63]
	v_pk_add_f32 v[62:63], v[66:67], 1.0 op_sel_hi:[1,0]
	v_pk_add_f32 v[66:67], v[72:73], 1.0 op_sel_hi:[1,0]
	v_rcp_f32_e32 v62, v62
	v_rcp_f32_e32 v66, v66
	v_rcp_f32_e32 v67, v67
	v_rcp_f32_e32 v63, v63
	v_pk_mul_f32 v[50:51], v[50:51], v[68:69] op_sel_hi:[1,0]
	v_cmp_gt_f32_e32 vcc, s25, v64
	v_pk_mul_f32 v[56:57], v[56:57], v[66:67]
	v_pk_mul_f32 v[58:59], v[58:59], v[62:63]
	v_pk_mul_f32 v[52:53], v[52:53], v[68:69] op_sel_hi:[1,0]
	v_pk_mul_f32 v[58:59], v[50:51], v[58:59]
	v_pk_mul_f32 v[50:51], v[48:49], v[56:57]
	v_mul_f32_e32 v48, 0x4b800000, v64
	v_cndmask_b32_e32 v48, v64, v48, vcc
	v_rsq_f32_e32 v56, v48
	v_pk_mul_f32 v[52:53], v[52:53], v[70:71]
	v_cvt_pk_bf16_f32 v50, v50, v51
	v_cvt_pk_bf16_f32 v48, v52, v53
	v_mul_f32_e32 v51, 0x45800000, v56
	v_cndmask_b32_e32 v52, v56, v51, vcc
	v_pk_mul_f32 v[44:45], v[44:45], v[52:53] op_sel_hi:[1,0]
	v_pk_mul_f32 v[46:47], v[46:47], v[52:53] op_sel_hi:[1,0]
	v_cvt_pk_bf16_f32 v49, v54, v55
	v_pk_mul_f32 v[54:55], v[46:47], s[38:39] op_sel_hi:[1,0]
	v_pk_mul_f32 v[56:57], v[44:45], s[38:39] op_sel_hi:[1,0]
	v_exp_f32_e32 v54, v54
	v_exp_f32_e32 v56, v56
	v_exp_f32_e32 v55, v55
	v_exp_f32_e32 v57, v57
	v_cvt_pk_bf16_f32 v51, v58, v59
	global_store_dwordx4 v[60:61], v[48:51], off nt
	v_pk_mul_f32 v[36:37], v[36:37], v[52:53] op_sel_hi:[1,0]
	v_pk_mul_f32 v[38:39], v[38:39], v[52:53] op_sel_hi:[1,0]
	v_pk_add_f32 v[48:49], v[54:55], 1.0 op_sel_hi:[1,0]
	v_pk_add_f32 v[50:51], v[56:57], 1.0 op_sel_hi:[1,0]
	v_rcp_f32_e32 v48, v48
	v_rcp_f32_e32 v50, v50
	v_rcp_f32_e32 v51, v51
	v_rcp_f32_e32 v49, v49
	v_pk_mul_f32 v[40:41], v[40:41], v[52:53] op_sel_hi:[1,0]
	v_pk_mul_f32 v[42:43], v[42:43], v[52:53] op_sel_hi:[1,0]
	v_pk_mul_f32 v[44:45], v[44:45], v[50:51]
	v_pk_mul_f32 v[46:47], v[46:47], v[48:49]
	s_waitcnt vmcnt(6)
	v_mov_b32_e32 v48, v133
	v_mov_b32_e32 v49, v134
	v_mov_b32_e32 v133, v135
	s_waitcnt vmcnt(5)
	v_mov_b32_e32 v50, v129
	v_mov_b32_e32 v51, v130
	v_mov_b32_e32 v129, v131
	v_pk_add_f32 v[48:49], v[48:49], v[132:133]
	v_pk_add_f32 v[50:51], v[50:51], v[128:129]
	v_pk_mul_f32 v[32:33], v[32:33], v[52:53] op_sel_hi:[1,0]
	v_pk_mul_f32 v[34:35], v[34:35], v[52:53] op_sel_hi:[1,0]
	v_mov_b32_e32 v52, v50
	v_mov_b32_e32 v53, v48
	v_mov_b32_e32 v48, v51
	v_pk_add_f32 v[48:49], v[52:53], v[48:49]
	v_pk_mul_f32 v[38:39], v[38:39], v[46:47]
	v_pk_mul_f32 v[36:37], v[36:37], v[44:45]
	v_pk_mul_f32 v[44:45], v[42:43], s[38:39] op_sel_hi:[1,0]
	v_pk_mul_f32 v[46:47], v[40:41], s[38:39] op_sel_hi:[1,0]
	ds_bpermute_b32 v51, v165, v49
	ds_bpermute_b32 v50, v165, v48
	v_exp_f32_e32 v46, v46
	v_exp_f32_e32 v44, v44
	v_exp_f32_e32 v45, v45
	v_exp_f32_e32 v47, v47
	s_waitcnt lgkmcnt(0)
; #define PG8_BAR __builtin_amdgcn_s_barrier()
; __device__ __forceinline__ v4u pack8(const float* x) { v4u o; o.x = pk2(x[0], x[1]); o.y = pk2(x[2], x[3]); o.z = pk2(x[4], x[5]); o.w = pk2(x[6], x[7]); return o; }
; __device__ __forceinline__ size_t tl(int row, int col, int K) { return (size_t)(row >> 8) * ((size_t)256 * K) + (size_t)(col >> 6) * (256 * 64) + (size_t)((row & 255) * 64 + (col & 63)); }
;     static __device__ __forceinline__ bool keep_acc(const Unit& u) { return (u.pm >> 6) == 2; }
; template <class Epi, class Sched, bool ALIGN_EPI = false, bool SP2 = false>
; __device__ __forceinline__ void gemm_phase(PG8_LAS unsigned char* lds, const Gemm g, const Sched& S, const Epi& E) {
;     ...
;         if constexpr (ALIGN_EPI) { if (wr == 0) PG8_BAR; }
;         const bool keep = Epi::keep_acc(cur);
;         if constexpr (!Epi::AFTER_DRAIN) { if (!keep) E(acc, cur, wr, wc, fr, fq); S.done(cur); }
;         if (!has_next) break;
;         if (!keep)
; #pragma unroll
;         for (int a = 0; a < 2; ++a)
; #pragma unroll
;             for (int b = 0; b < 2; ++b)
; #pragma unroll
;                 for (int m = 0; m < 4; ++m)
; #pragma unroll
;                     for (int n = 0; n < 2; ++n) acc[a][b][m][n] = (f32x4){0.f, 0.f, 0.f, 0.f};
;         cur = nxt; cA = nA; cB = nB; ++ui;
;         if constexpr (ALIGN_EPI) { if (wr == 1) PG8_BAR; }
;     __device__ __forceinline__ void operator()(const f32x4 (&acc)[2][2][4][2], const Unit& u, int wr, int wc, int, int) const {
;     ...
;             for (int m = 0; m < 4; ++m) {
;                 const int row = row0 + ai * HALF + m * 16; const float rs = rstd_from_quarter(pq[ai][m], fq * 16 + fr);
;                 float h[8];
; #pragma unroll
;                 for (int n = 0; n < 2; ++n) { const f32x4 g = acc[ai][0][m][n] * rs, uu = acc[ai][1][m][n] * rs; const f32x4 hv = (g * sigmoid4(g)) * uu;
;                     h[n * 4 + 0] = hv[0]; h[n * 4 + 1] = hv[1]; h[n * 4 + 2] = hv[2]; h[n * 4 + 3] = hv[3]; }
;                 __builtin_nontemporal_store(pack8(h), (u32x4*)(O + tl(row, col0, FF)));
;             }
	v_pk_add_f32 v[48:49], v[48:49], v[50:51]
	ds_bpermute_b32 v51, v164, v49
	v_pk_add_f32 v[44:45], v[44:45], 1.0 op_sel_hi:[1,0]
	v_pk_add_f32 v[46:47], v[46:47], 1.0 op_sel_hi:[1,0]
	v_rcp_f32_e32 v44, v44
	v_rcp_f32_e32 v46, v46
	v_rcp_f32_e32 v47, v47
	v_rcp_f32_e32 v45, v45
	ds_bpermute_b32 v50, v164, v48
	v_pk_mul_f32 v[40:41], v[40:41], v[46:47]
	v_pk_mul_f32 v[42:43], v[42:43], v[44:45]
	s_nop 0
	v_pk_mul_f32 v[42:43], v[34:35], v[42:43]
	v_pk_mul_f32 v[34:35], v[32:33], v[40:41]
	s_waitcnt lgkmcnt(0)
	v_pk_add_f32 v[32:33], v[48:49], v[50:51]
	v_cvt_pk_bf16_f32 v34, v34, v35
	v_pk_fma_f32 v[40:41], v[32:33], s[74:75], v[156:157] op_sel_hi:[1,0,0]
	v_cvt_pk_bf16_f32 v33, v38, v39
	v_mul_f32_e32 v32, 0x4b800000, v41
	v_cmp_gt_f32_e32 vcc, s25, v41
	s_nop 1
	v_cndmask_b32_e32 v32, v41, v32, vcc
	v_rsq_f32_e32 v41, v32
	v_cvt_pk_bf16_f32 v32, v36, v37
	v_mul_f32_e32 v35, 0x45800000, v41
	v_cndmask_b32_e32 v36, v41, v35, vcc
	v_pk_mul_f32 v[28:29], v[28:29], v[36:37] op_sel_hi:[1,0]
	v_pk_mul_f32 v[30:31], v[30:31], v[36:37] op_sel_hi:[1,0]
	v_pk_mul_f32 v[44:45], v[28:29], s[38:39] op_sel_hi:[1,0]
	v_pk_mul_f32 v[38:39], v[30:31], s[38:39] op_sel_hi:[1,0]
	v_exp_f32_e32 v44, v44
	v_exp_f32_e32 v38, v38
	v_exp_f32_e32 v39, v39
	v_exp_f32_e32 v45, v45
	v_cvt_pk_bf16_f32 v35, v42, v43
	global_store_dwordx4 v[60:61], v[32:35], off offset:2048 nt
	v_pk_mul_f32 v[24:25], v[24:25], v[36:37] op_sel_hi:[1,0]
	v_pk_mul_f32 v[26:27], v[26:27], v[36:37] op_sel_hi:[1,0]
	v_pk_add_f32 v[32:33], v[38:39], 1.0 op_sel_hi:[1,0]
	v_pk_add_f32 v[34:35], v[44:45], 1.0 op_sel_hi:[1,0]
	v_rcp_f32_e32 v32, v32
	v_rcp_f32_e32 v34, v34
	v_rcp_f32_e32 v35, v35
	v_rcp_f32_e32 v33, v33
	v_pk_mul_f32 v[20:21], v[20:21], v[36:37] op_sel_hi:[1,0]
	v_pk_mul_f32 v[22:23], v[22:23], v[36:37] op_sel_hi:[1,0]
	v_pk_mul_f32 v[28:29], v[28:29], v[34:35]
	v_pk_mul_f32 v[30:31], v[30:31], v[32:33]
	v_pk_mul_f32 v[32:33], v[26:27], s[38:39] op_sel_hi:[1,0]
	v_pk_mul_f32 v[34:35], v[24:25], s[38:39] op_sel_hi:[1,0]
	v_exp_f32_e32 v32, v32
	v_exp_f32_e32 v34, v34
	v_exp_f32_e32 v33, v33
	v_exp_f32_e32 v35, v35
	v_pk_mul_f32 v[22:23], v[22:23], v[30:31]
	v_pk_mul_f32 v[20:21], v[20:21], v[28:29]
	v_pk_add_f32 v[28:29], v[32:33], 1.0 op_sel_hi:[1,0]
	v_pk_add_f32 v[30:31], v[34:35], 1.0 op_sel_hi:[1,0]
	v_rcp_f32_e32 v28, v28
	v_rcp_f32_e32 v30, v30
	v_rcp_f32_e32 v31, v31
	v_rcp_f32_e32 v29, v29
	v_pk_mul_f32 v[16:17], v[16:17], v[36:37] op_sel_hi:[1,0]
	v_pk_mul_f32 v[18:19], v[18:19], v[36:37] op_sel_hi:[1,0]
	v_pk_mul_f32 v[24:25], v[24:25], v[30:31]
	v_pk_mul_f32 v[26:27], v[26:27], v[28:29]
	v_cmp_gt_f32_e32 vcc, s25, v40
	v_pk_mul_f32 v[26:27], v[18:19], v[26:27]
	v_pk_mul_f32 v[18:19], v[16:17], v[24:25]
	v_mul_f32_e32 v17, 0x4b800000, v40
	v_cndmask_b32_e32 v17, v40, v17, vcc
	v_cvt_pk_bf16_f32 v16, v20, v21
	v_rsq_f32_e32 v20, v17
	v_cvt_pk_bf16_f32 v17, v22, v23
	v_cvt_pk_bf16_f32 v18, v18, v19
	v_cvt_pk_bf16_f32 v19, v26, v27
	v_mul_f32_e32 v21, 0x45800000, v20
	v_cndmask_b32_e32 v20, v20, v21, vcc
	v_pk_mul_f32 v[12:13], v[12:13], v[20:21] op_sel_hi:[1,0]
	v_pk_mul_f32 v[14:15], v[14:15], v[20:21] op_sel_hi:[1,0]
	v_pk_mul_f32 v[24:25], v[12:13], s[38:39] op_sel_hi:[1,0]
	v_pk_mul_f32 v[22:23], v[14:15], s[38:39] op_sel_hi:[1,0]
	v_exp_f32_e32 v24, v24
	v_exp_f32_e32 v25, v25
	v_exp_f32_e32 v22, v22
	v_exp_f32_e32 v23, v23
	v_add_co_u32_e32 v26, vcc, s85, v60
	v_pk_mul_f32 v[8:9], v[8:9], v[20:21] op_sel_hi:[1,0]
	s_nop 0
	v_addc_co_u32_e32 v27, vcc, 0, v61, vcc
	global_store_dwordx4 v[26:27], v[16:19], off nt
	v_pk_mul_f32 v[10:11], v[10:11], v[20:21] op_sel_hi:[1,0]
	v_pk_mul_f32 v[4:5], v[4:5], v[20:21] op_sel_hi:[1,0]
	v_pk_add_f32 v[16:17], v[22:23], 1.0 op_sel_hi:[1,0]
	v_pk_add_f32 v[18:19], v[24:25], 1.0 op_sel_hi:[1,0]
	v_rcp_f32_e32 v16, v16
	v_rcp_f32_e32 v18, v18
	v_rcp_f32_e32 v19, v19
	v_rcp_f32_e32 v17, v17
	v_pk_mul_f32 v[6:7], v[6:7], v[20:21] op_sel_hi:[1,0]
	v_pk_mul_f32 v[0:1], v[0:1], v[20:21] op_sel_hi:[1,0]
	v_pk_mul_f32 v[12:13], v[12:13], v[18:19]
	v_pk_mul_f32 v[14:15], v[14:15], v[16:17]
	v_pk_mul_f32 v[16:17], v[10:11], s[38:39] op_sel_hi:[1,0]
	v_pk_mul_f32 v[18:19], v[8:9], s[38:39] op_sel_hi:[1,0]
	v_exp_f32_e32 v16, v16
	v_exp_f32_e32 v18, v18
	v_exp_f32_e32 v17, v17
	v_exp_f32_e32 v19, v19
	v_pk_mul_f32 v[6:7], v[6:7], v[14:15]
	v_pk_mul_f32 v[4:5], v[4:5], v[12:13]
	v_pk_add_f32 v[12:13], v[16:17], 1.0 op_sel_hi:[1,0]
	v_pk_add_f32 v[14:15], v[18:19], 1.0 op_sel_hi:[1,0]
	v_rcp_f32_e32 v12, v12
	v_rcp_f32_e32 v14, v14
	v_rcp_f32_e32 v15, v15
	v_rcp_f32_e32 v13, v13
	v_pk_mul_f32 v[2:3], v[2:3], v[20:21] op_sel_hi:[1,0]
	s_andn2_b64 vcc, exec, s[2:3]
	v_pk_mul_f32 v[8:9], v[8:9], v[14:15]
	v_pk_mul_f32 v[10:11], v[10:11], v[12:13]
	s_mov_b64 s[2:3], -1
	v_pk_mul_f32 v[10:11], v[2:3], v[10:11]
	v_pk_mul_f32 v[2:3], v[0:1], v[8:9]
	v_cvt_pk_bf16_f32 v0, v4, v5
	v_cvt_pk_bf16_f32 v1, v6, v7
	v_cvt_pk_bf16_f32 v2, v2, v3
	v_cvt_pk_bf16_f32 v3, v10, v11
	global_store_dwordx4 v[26:27], v[0:3], off offset:2048 nt
	s_cbranch_vccnz .LBB0_1352
	s_branch .LBB0_1351
